# last-unit tail prefetch (never read) now targets the matrix first tiles so every workgroup hits the same L2 lines
# baseline (speedup 1.0000x reference)
;     __device__ bool next(int i, Unit& u) const { if (!base.next(i / 3, u)) return false; u.seg = i % 3; return true; }
; #define PG8_UNIT(u, a, b, ntu) do { int _k0 = 0; ntu = nt; if constexpr (Epi::SEG3) { _k0 = (u).seg == 0 ? 0 : ((u).seg == 1 ? 384 : 640); ntu = (u).seg == 1 ? 4 : 6; } \
;         a = (const char*)g.A + (size_t)(u).pm * tstep + (size_t)_k0 * 2; b = (const char*)g.Bt + (size_t)(u).pn * tstep + (size_t)_k0 * 2; } while (0)
; template <class Epi, class Sched>
; __device__ __forceinline__ void gemm_phase(LAS unsigned char* lds, const Gemm g, const Sched& S, const Epi& E) {
;     ...
;         const bool has_next = S.next(ui + 1, nxt);
;         const char* nA = cA; const char* nB = cB; int nnt = cnt; if (has_next) PG8_UNIT(nxt, nA, nB, nnt);
;         for (int t = 0; t < cnt; t += 2) {
;             const bool last = (t == cnt - 2);
;             const char* a1 = cA + (size_t)(t + 1) * kstep;
;             const char* a2 = last ? nA : cA + (size_t)(t + 2) * kstep; const char* b2 = last ? nB : cB + (size_t)(t + 2) * kstep;
;     ...
;         for (int a = 0; a < 2; ++a)
; #pragma unroll
;             for (int b = 0; b < 2; ++b)
; #pragma unroll
;                 for (int m = 0; m < 4; ++m)
; #pragma unroll
;                     for (int n = 0; n < 2; ++n) acc[a][b][m][n] = (f32x4){0.f, 0.f, 0.f, 0.f};
.LBB0_192:
	s_ashr_i32 s21, s20, 31
	s_lshl_b64 s[6:7], s[20:21], 19
	s_add_u32 s26, s0, s6
	s_addc_u32 s27, s1, s7
	s_ashr_i32 s23, s22, 31
	s_lshl_b64 s[6:7], s[22:23], 19
	s_add_u32 s28, s37, s6
	s_addc_u32 s29, s42, s7
	s_and_b64 s[6:7], s[24:25], exec
	s_cselect_b32 s21, s27, s1
	s_cselect_b32 s23, s26, s0
	s_cselect_b32 s34, s29, s42
	s_cselect_b32 s35, s28, s37
	s_add_u32 s39, s2, 0x100
	s_addc_u32 s62, s3, 0
	s_add_u32 s2, s4, 0x40080
	v_mov_b32_e32 v2, 0
	s_addc_u32 s3, s5, 0
	s_mov_b32 s63, -2
	v_mov_b32_e32 v3, v2
	v_mov_b32_e32 v4, v2
	v_mov_b32_e32 v5, v2
	v_mov_b32_e32 v6, v2
	v_mov_b32_e32 v7, v2
	v_mov_b32_e32 v8, v2
	v_mov_b32_e32 v9, v2
	v_mov_b32_e32 v18, v2
	v_mov_b32_e32 v19, v2
	v_mov_b32_e32 v20, v2
	v_mov_b32_e32 v21, v2
	v_mov_b32_e32 v22, v2
	v_mov_b32_e32 v23, v2
	v_mov_b32_e32 v24, v2
	v_mov_b32_e32 v25, v2
	v_mov_b32_e32 v34, v2
	v_mov_b32_e32 v35, v2
	v_mov_b32_e32 v36, v2
	v_mov_b32_e32 v37, v2
	v_mov_b32_e32 v38, v2
	v_mov_b32_e32 v39, v2
	s_waitcnt vmcnt(0)
	v_mov_b32_e32 v40, v2
	v_mov_b32_e32 v41, v2
	v_mov_b32_e32 v50, v2
	v_mov_b32_e32 v51, v2
	v_mov_b32_e32 v52, v2
	v_mov_b32_e32 v53, v2
	v_mov_b32_e32 v54, v2
	v_mov_b32_e32 v55, v2
	v_mov_b32_e32 v56, v2
	v_mov_b32_e32 v57, v2
	v_mov_b32_e32 v10, v2
	v_mov_b32_e32 v11, v2
	v_mov_b32_e32 v12, v2
	v_mov_b32_e32 v13, v2
	v_mov_b32_e32 v14, v2
	v_mov_b32_e32 v15, v2
	v_mov_b32_e32 v16, v2
	v_mov_b32_e32 v17, v2
	v_mov_b32_e32 v26, v2
	v_mov_b32_e32 v27, v2
	v_mov_b32_e32 v28, v2
	v_mov_b32_e32 v29, v2
	v_mov_b32_e32 v30, v2
	v_mov_b32_e32 v31, v2
	v_mov_b32_e32 v32, v2
	v_mov_b32_e32 v33, v2
	v_mov_b32_e32 v42, v2
	v_mov_b32_e32 v43, v2
	v_mov_b32_e32 v44, v2
	v_mov_b32_e32 v45, v2
	v_mov_b32_e32 v46, v2
	v_mov_b32_e32 v47, v2
	v_mov_b32_e32 v48, v2
	v_mov_b32_e32 v49, v2
	v_mov_b32_e32 v58, v2
	v_mov_b32_e32 v59, v2
	v_mov_b32_e32 v60, v2
	v_mov_b32_e32 v61, v2
	v_mov_b32_e32 v62, v2
	v_mov_b32_e32 v63, v2
	v_mov_b32_e32 v64, v2
	v_mov_b32_e32 v65, v2
	v_mov_b32_e32 v66, v2
	v_mov_b32_e32 v67, v2
	v_mov_b32_e32 v68, v2
	v_mov_b32_e32 v69, v2
	v_mov_b32_e32 v70, v2
	v_mov_b32_e32 v71, v2
	v_mov_b32_e32 v72, v2
	v_mov_b32_e32 v73, v2
	v_mov_b32_e32 v82, v2
	v_mov_b32_e32 v83, v2
	v_mov_b32_e32 v84, v2
	v_mov_b32_e32 v85, v2
	v_mov_b32_e32 v86, v2
	v_mov_b32_e32 v87, v2
	v_mov_b32_e32 v88, v2
	v_mov_b32_e32 v89, v2
	v_mov_b32_e32 v98, v2
	v_mov_b32_e32 v99, v2
	v_mov_b32_e32 v100, v2
	v_mov_b32_e32 v101, v2
	v_mov_b32_e32 v102, v2
	v_mov_b32_e32 v103, v2
	v_mov_b32_e32 v104, v2
	v_mov_b32_e32 v105, v2
	v_mov_b32_e32 v114, v2
	v_mov_b32_e32 v115, v2
	v_mov_b32_e32 v116, v2
	v_mov_b32_e32 v117, v2
	v_mov_b32_e32 v118, v2
	v_mov_b32_e32 v119, v2
	v_mov_b32_e32 v120, v2
	v_mov_b32_e32 v121, v2
	v_mov_b32_e32 v74, v2
	v_mov_b32_e32 v75, v2
	v_mov_b32_e32 v76, v2
	v_mov_b32_e32 v77, v2
	v_mov_b32_e32 v78, v2
	v_mov_b32_e32 v79, v2
	v_mov_b32_e32 v80, v2
	v_mov_b32_e32 v81, v2
	v_mov_b32_e32 v90, v2
	v_mov_b32_e32 v91, v2
	v_mov_b32_e32 v92, v2
	v_mov_b32_e32 v93, v2
	v_mov_b32_e32 v94, v2
	v_mov_b32_e32 v95, v2
	v_mov_b32_e32 v96, v2
	v_mov_b32_e32 v97, v2
	v_mov_b32_e32 v106, v2
	v_mov_b32_e32 v107, v2
	v_mov_b32_e32 v108, v2
	v_mov_b32_e32 v109, v2
	v_mov_b32_e32 v110, v2
	v_mov_b32_e32 v111, v2
	v_mov_b32_e32 v112, v2
	v_mov_b32_e32 v113, v2
	v_mov_b32_e32 v122, v2
	v_mov_b32_e32 v123, v2
	v_mov_b32_e32 v124, v2
	v_mov_b32_e32 v125, v2
	v_mov_b32_e32 v126, v2
	v_mov_b32_e32 v127, v2
	v_mov_b32_e32 v128, v2
	v_mov_b32_e32 v129, v2

;     __device__ bool next(int i, Unit& u) const { if (!base.next(i / 3, u)) return false; u.seg = i % 3; return true; }
; #define PG8_STAGE(bufoff, gbase, voff) do { _Pragma("unroll") for (int _i = 0; _i < 2; ++_i) \
;         __builtin_amdgcn_global_load_lds((const unsigned*)((const char*)(gbase) + (voff)[_i]), (LAS unsigned*)(lds + (bufoff) + ldsw + _i * 8192), 16, 0, 0); } while (0)
; #define PG8_WAIT_V(n) asm volatile("s_waitcnt vmcnt(" #n ")" ::: "memory")
; #define PG8_BAR __builtin_amdgcn_s_barrier()
; #define PG8_UNIT(u, a, b, ntu) do { int _k0 = 0; ntu = nt; if constexpr (Epi::SEG3) { _k0 = (u).seg == 0 ? 0 : ((u).seg == 1 ? 384 : 640); ntu = (u).seg == 1 ? 4 : 6; } \
;         a = (const char*)g.A + (size_t)(u).pm * tstep + (size_t)_k0 * 2; b = (const char*)g.Bt + (size_t)(u).pn * tstep + (size_t)_k0 * 2; } while (0)
; template <class Epi, class Sched>
; __device__ __forceinline__ void gemm_phase(LAS unsigned char* lds, const Gemm g, const Sched& S, const Epi& E) {
;     ...
;     const char* cA; const char* cB; int cnt; PG8_UNIT(cur, cA, cB, cnt);
;     PG8_STAGE(PG8_SB(0, 0), cB, voffB); PG8_STAGE(PG8_SB(0, 1), cB + hstepB, voffB); PG8_STAGE(PG8_SA(0, 0), cA, voffA); PG8_STAGE(PG8_SA(0, 1), cA + hstepA, voffA);
;     if (wr == 1) PG8_BAR;
;     PG8_WAIT_V(2); PG8_BAR;
;     PG8_STAGE(PG8_SB(1, 0), cB + kstep, voffB); PG8_STAGE(PG8_SA(1, 0), cA + kstep, voffA); PG8_STAGE(PG8_SB(1, 1), cB + hstepB + kstep, voffB);
;     PG8_WAIT_V(6); PG8_BAR;
;     for (;;) {
;         const bool has_next = S.next(ui + 1, nxt);
;         const char* nA = cA; const char* nB = cB; int nnt = cnt; if (has_next) PG8_UNIT(nxt, nA, nB, nnt);
.LBB0_741:
	v_cndmask_b32_e64 v2, 0, 1, s[18:19]
	v_cmp_ne_u32_e64 s[4:5], 1, v2
	s_andn2_b64 vcc, exec, s[18:19]
	s_mov_b32 s18, s1
	s_mov_b32 s19, s26
	s_mov_b32 s20, s27
	s_mov_b32 s21, s28
	s_mov_b32 s56, s57
	s_cbranch_vccnz .LBB0_743
	s_cmp_eq_u32 s51, 1
	s_movk_i32 s15, 0x500
	s_cselect_b32 s15, 0x300, s15
	s_cselect_b32 s56, 4, 6
	s_cmp_lg_u32 s51, 0
	s_cselect_b32 s24, s15, 0
	s_ashr_i32 s15, s14, 31
	s_lshl_b64 s[18:19], s[14:15], 19
	s_add_u32 s15, s1, s18
	s_addc_u32 s17, s26, s19
	s_add_u32 s18, s15, s24
	s_addc_u32 s19, s17, 0
	s_ashr_i32 s17, s16, 31
	s_lshl_b64 s[20:21], s[16:17], 19
	s_add_u32 s15, s27, s20
	s_addc_u32 s17, s28, s21
	s_add_u32 s20, s15, s24
	s_addc_u32 s21, s17, 0

;     __device__ bool next(int i, Unit& u) const { if (!base.next(i / 3, u)) return false; u.seg = i % 3; return true; }
; #define PG8_STAGE(bufoff, gbase, voff) do { _Pragma("unroll") for (int _i = 0; _i < 2; ++_i) \
;         __builtin_amdgcn_global_load_lds((const unsigned*)((const char*)(gbase) + (voff)[_i]), (LAS unsigned*)(lds + (bufoff) + ldsw + _i * 8192), 16, 0, 0); } while (0)
; #define PG8_WAIT_V(n) asm volatile("s_waitcnt vmcnt(" #n ")" ::: "memory")
; #define PG8_BAR __builtin_amdgcn_s_barrier()
; #define PG8_UNIT(u, a, b, ntu) do { int _k0 = 0; ntu = nt; if constexpr (Epi::SEG3) { _k0 = (u).seg == 0 ? 0 : ((u).seg == 1 ? 384 : 640); ntu = (u).seg == 1 ? 4 : 6; } \
;         a = (const char*)g.A + (size_t)(u).pm * tstep + (size_t)_k0 * 2; b = (const char*)g.Bt + (size_t)(u).pn * tstep + (size_t)_k0 * 2; } while (0)
; template <class Epi, class Sched>
; __device__ __forceinline__ void gemm_phase(LAS unsigned char* lds, const Gemm g, const Sched& S, const Epi& E) {
;     ...
;     const char* cA; const char* cB; int cnt; PG8_UNIT(cur, cA, cB, cnt);
;     PG8_STAGE(PG8_SB(0, 0), cB, voffB); PG8_STAGE(PG8_SB(0, 1), cB + hstepB, voffB); PG8_STAGE(PG8_SA(0, 0), cA, voffA); PG8_STAGE(PG8_SA(0, 1), cA + hstepA, voffA);
;     if (wr == 1) PG8_BAR;
;     PG8_WAIT_V(2); PG8_BAR;
;     PG8_STAGE(PG8_SB(1, 0), cB + kstep, voffB); PG8_STAGE(PG8_SA(1, 0), cA + kstep, voffA); PG8_STAGE(PG8_SB(1, 1), cB + hstepB + kstep, voffB);
;     PG8_WAIT_V(6); PG8_BAR;
;     for (;;) {
;         const bool has_next = S.next(ui + 1, nxt);
;         const char* nA = cA; const char* nB = cB; int nnt = cnt; if (has_next) PG8_UNIT(nxt, nA, nB, nnt);
.LBB0_841:
	v_cndmask_b32_e64 v0, 0, 1, s[20:21]
	v_cmp_ne_u32_e64 s[4:5], 1, v0
	s_andn2_b64 vcc, exec, s[20:21]
	s_mov_b32 s20, s1
	s_mov_b32 s21, s28
	s_mov_b32 s22, s29
	s_mov_b32 s23, s30
	s_cbranch_vccnz .LBB0_843
	s_ashr_i32 s17, s16, 31
	s_lshl_b64 s[20:21], s[16:17], 19
	s_add_u32 s20, s1, s20
	s_addc_u32 s21, s28, s21
	s_ashr_i32 s19, s18, 31
	s_lshl_b64 s[22:23], s[18:19], 19
	s_add_u32 s22, s29, s22
	s_addc_u32 s23, s30, s23

;     __device__ bool next(int i, Unit& u) const { if (!base.next(i / 3, u)) return false; u.seg = i % 3; return true; }
; #define PG8_UNIT(u, a, b, ntu) do { int _k0 = 0; ntu = nt; if constexpr (Epi::SEG3) { _k0 = (u).seg == 0 ? 0 : ((u).seg == 1 ? 384 : 640); ntu = (u).seg == 1 ? 4 : 6; } \
;         a = (const char*)g.A + (size_t)(u).pm * tstep + (size_t)_k0 * 2; b = (const char*)g.Bt + (size_t)(u).pn * tstep + (size_t)_k0 * 2; } while (0)
; template <class Epi, class Sched>
; __device__ __forceinline__ void gemm_phase(LAS unsigned char* lds, const Gemm g, const Sched& S, const Epi& E) {
;     ...
;         const bool has_next = S.next(ui + 1, nxt);
;         const char* nA = cA; const char* nB = cB; int nnt = cnt; if (has_next) PG8_UNIT(nxt, nA, nB, nnt);
;         for (int t = 0; t < cnt; t += 2) {
;             const bool last = (t == cnt - 2);
;             const char* a1 = cA + (size_t)(t + 1) * kstep;
;             const char* a2 = last ? nA : cA + (size_t)(t + 2) * kstep; const char* b2 = last ? nB : cB + (size_t)(t + 2) * kstep;
;     ...
;         for (int a = 0; a < 2; ++a)
; #pragma unroll
;             for (int b = 0; b < 2; ++b)
; #pragma unroll
;                 for (int m = 0; m < 4; ++m)
; #pragma unroll
;                     for (int n = 0; n < 2; ++n) acc[a][b][m][n] = (f32x4){0.f, 0.f, 0.f, 0.f};
.LBB0_923:
	s_ashr_i32 s13, s12, 31
	s_lshl_b64 s[18:19], s[12:13], 19
	s_add_u32 s18, s1, s18
	s_addc_u32 s19, s28, s19
	s_ashr_i32 s15, s14, 31
	s_lshl_b64 s[20:21], s[14:15], 19
	s_add_u32 s20, s29, s20
	s_addc_u32 s21, s30, s21
	s_and_b64 s[26:27], s[16:17], exec
	s_cselect_b32 s13, s19, s28
	s_cselect_b32 s15, s18, s1
	s_cselect_b32 s39, s21, s30
	s_cselect_b32 s57, s20, s29
	s_add_u32 s62, s22, 0x100
	s_addc_u32 s63, s23, 0
	s_add_u32 s22, s24, 0x40080
	v_mov_b32_e32 v2, 0
	s_addc_u32 s23, s25, 0
	s_mov_b32 s64, -2
	v_mov_b32_e32 v3, v2
	v_mov_b32_e32 v4, v2
	v_mov_b32_e32 v5, v2
	v_mov_b32_e32 v6, v2
	v_mov_b32_e32 v7, v2
	v_mov_b32_e32 v8, v2
	v_mov_b32_e32 v9, v2
	v_mov_b32_e32 v18, v2
	v_mov_b32_e32 v19, v2
	v_mov_b32_e32 v20, v2
	v_mov_b32_e32 v21, v2
	v_mov_b32_e32 v22, v2
	v_mov_b32_e32 v23, v2
	v_mov_b32_e32 v24, v2
	v_mov_b32_e32 v25, v2
	v_mov_b32_e32 v34, v2
	v_mov_b32_e32 v35, v2
	v_mov_b32_e32 v36, v2
	v_mov_b32_e32 v37, v2
	v_mov_b32_e32 v38, v2
	v_mov_b32_e32 v39, v2
	v_mov_b32_e32 v40, v2
	v_mov_b32_e32 v41, v2
	v_mov_b32_e32 v50, v2
	v_mov_b32_e32 v51, v2
	v_mov_b32_e32 v52, v2
	v_mov_b32_e32 v53, v2
	v_mov_b32_e32 v54, v2
	v_mov_b32_e32 v55, v2
	v_mov_b32_e32 v56, v2
	v_mov_b32_e32 v57, v2
	v_mov_b32_e32 v10, v2
	v_mov_b32_e32 v11, v2
	v_mov_b32_e32 v12, v2
	v_mov_b32_e32 v13, v2
	v_mov_b32_e32 v14, v2
	v_mov_b32_e32 v15, v2
	v_mov_b32_e32 v16, v2
	v_mov_b32_e32 v17, v2
	v_mov_b32_e32 v26, v2
	v_mov_b32_e32 v27, v2
	v_mov_b32_e32 v28, v2
	v_mov_b32_e32 v29, v2
	v_mov_b32_e32 v30, v2
	v_mov_b32_e32 v31, v2
	v_mov_b32_e32 v32, v2
	v_mov_b32_e32 v33, v2
	v_mov_b32_e32 v42, v2
	v_mov_b32_e32 v43, v2
	v_mov_b32_e32 v44, v2
	v_mov_b32_e32 v45, v2
	v_mov_b32_e32 v46, v2
	v_mov_b32_e32 v47, v2
	v_mov_b32_e32 v48, v2
	v_mov_b32_e32 v49, v2
	v_mov_b32_e32 v58, v2
	v_mov_b32_e32 v59, v2
	v_mov_b32_e32 v60, v2
	v_mov_b32_e32 v61, v2
	v_mov_b32_e32 v62, v2
	v_mov_b32_e32 v63, v2
	v_mov_b32_e32 v64, v2
	v_mov_b32_e32 v65, v2
	v_mov_b32_e32 v66, v2
	v_mov_b32_e32 v67, v2
	v_mov_b32_e32 v68, v2
	v_mov_b32_e32 v69, v2
	v_mov_b32_e32 v70, v2
	v_mov_b32_e32 v71, v2
	v_mov_b32_e32 v72, v2
	v_mov_b32_e32 v73, v2
	v_mov_b32_e32 v82, v2
	v_mov_b32_e32 v83, v2
	v_mov_b32_e32 v84, v2
	v_mov_b32_e32 v85, v2
	v_mov_b32_e32 v86, v2
	v_mov_b32_e32 v87, v2
	v_mov_b32_e32 v88, v2
	v_mov_b32_e32 v89, v2
	v_mov_b32_e32 v98, v2
	v_mov_b32_e32 v99, v2
	v_mov_b32_e32 v100, v2
	v_mov_b32_e32 v101, v2
	v_mov_b32_e32 v102, v2
	v_mov_b32_e32 v103, v2
	v_mov_b32_e32 v104, v2
	v_mov_b32_e32 v105, v2
	v_mov_b32_e32 v114, v2
	v_mov_b32_e32 v115, v2
	v_mov_b32_e32 v116, v2
	v_mov_b32_e32 v117, v2
	v_mov_b32_e32 v118, v2
	v_mov_b32_e32 v119, v2
	v_mov_b32_e32 v120, v2
	v_mov_b32_e32 v121, v2
	v_mov_b32_e32 v74, v2
	v_mov_b32_e32 v75, v2
	v_mov_b32_e32 v76, v2
	v_mov_b32_e32 v77, v2
	v_mov_b32_e32 v78, v2
	v_mov_b32_e32 v79, v2
	v_mov_b32_e32 v80, v2
	v_mov_b32_e32 v81, v2
	v_mov_b32_e32 v90, v2
	v_mov_b32_e32 v91, v2
	v_mov_b32_e32 v92, v2
	v_mov_b32_e32 v93, v2
	v_mov_b32_e32 v94, v2
	v_mov_b32_e32 v95, v2
	v_mov_b32_e32 v96, v2
	v_mov_b32_e32 v97, v2
	v_mov_b32_e32 v106, v2
	v_mov_b32_e32 v107, v2
	v_mov_b32_e32 v108, v2
	v_mov_b32_e32 v109, v2
	v_mov_b32_e32 v110, v2
	v_mov_b32_e32 v111, v2
	v_mov_b32_e32 v112, v2
	v_mov_b32_e32 v113, v2
	v_mov_b32_e32 v122, v2
	v_mov_b32_e32 v123, v2
	v_mov_b32_e32 v124, v2
	v_mov_b32_e32 v125, v2
	v_mov_b32_e32 v126, v2
	v_mov_b32_e32 v127, v2
	v_mov_b32_e32 v128, v2
	v_mov_b32_e32 v129, v2

;     __device__ bool next(int i, Unit& u) const { if (!base.next(i / 3, u)) return false; u.seg = i % 3; return true; }
; #define PG8_STAGE(bufoff, gbase, voff) do { _Pragma("unroll") for (int _i = 0; _i < 2; ++_i) \
;         __builtin_amdgcn_global_load_lds((const unsigned*)((const char*)(gbase) + (voff)[_i]), (LAS unsigned*)(lds + (bufoff) + ldsw + _i * 8192), 16, 0, 0); } while (0)
; #define PG8_WAIT_V(n) asm volatile("s_waitcnt vmcnt(" #n ")" ::: "memory")
; #define PG8_BAR __builtin_amdgcn_s_barrier()
; #define PG8_UNIT(u, a, b, ntu) do { int _k0 = 0; ntu = nt; if constexpr (Epi::SEG3) { _k0 = (u).seg == 0 ? 0 : ((u).seg == 1 ? 384 : 640); ntu = (u).seg == 1 ? 4 : 6; } \
;         a = (const char*)g.A + (size_t)(u).pm * tstep + (size_t)_k0 * 2; b = (const char*)g.Bt + (size_t)(u).pn * tstep + (size_t)_k0 * 2; } while (0)
; template <class Epi, class Sched>
; __device__ __forceinline__ void gemm_phase(LAS unsigned char* lds, const Gemm g, const Sched& S, const Epi& E) {
;     ...
;     const char* cA; const char* cB; int cnt; PG8_UNIT(cur, cA, cB, cnt);
;     PG8_STAGE(PG8_SB(0, 0), cB, voffB); PG8_STAGE(PG8_SB(0, 1), cB + hstepB, voffB); PG8_STAGE(PG8_SA(0, 0), cA, voffA); PG8_STAGE(PG8_SA(0, 1), cA + hstepA, voffA);
;     if (wr == 1) PG8_BAR;
;     PG8_WAIT_V(2); PG8_BAR;
;     PG8_STAGE(PG8_SB(1, 0), cB + kstep, voffB); PG8_STAGE(PG8_SA(1, 0), cA + kstep, voffA); PG8_STAGE(PG8_SB(1, 1), cB + hstepB + kstep, voffB);
;     PG8_WAIT_V(6); PG8_BAR;
;     for (;;) {
;         const bool has_next = S.next(ui + 1, nxt);
;         const char* nA = cA; const char* nB = cB; int nnt = cnt; if (has_next) PG8_UNIT(nxt, nA, nB, nnt);
.LBB0_988:
	v_cndmask_b32_e64 v0, 0, 1, s[14:15]
	v_cmp_ne_u32_e64 s[2:3], 1, v0
	s_andn2_b64 vcc, exec, s[14:15]
	s_mov_b32 s14, s1
	s_mov_b32 s15, s24
	s_mov_b32 s16, s25
	s_mov_b32 s17, s26
	s_cbranch_vccnz .LBB0_990
	s_mul_i32 s14, s48, 0x208000
	s_mul_hi_i32 s15, s48, 0x208000
	s_add_u32 s14, s1, s14
	s_addc_u32 s15, s24, s15
	s_mul_i32 s16, s43, 0x208000
	s_mul_hi_i32 s17, s43, 0x208000
	s_add_u32 s16, s25, s16
	s_addc_u32 s17, s26, s17
